# Infinity-Cache touch of the next layer's f32 weights from the FFN-up tile epilogues (one 8 KB nt touch per participating wave and tile), so the FFN-down conversion tail reads them on-die
# baseline (speedup 1.0000x reference)
; #define PG8_LAS __attribute__((address_space(3)))
; __device__ __forceinline__ f32x4 vsilu(const f32x4& x) { return x * vsig(x); }
; #define EPV_K(dst1, dst2) do { _Pragma("unroll") for (int bj = 0; bj < 2; ++bj) _Pragma("unroll") for (int n = 0; n < 2; ++n) { \
;         dst1[bj][n] = *(const PG8_LAS f32x4*)(ev + 2048 + (wc * 32 + 8 * fq + bj * HALF + 4 * n) * 4); dst2[bj][n] = *(const PG8_LAS f32x4*)(ev + 3072 + (wc * 32 + 8 * fq + bj * HALF + 4 * n) * 4); } } while (0)
; __device__ __forceinline__ void st16_sel(void* p, u32x4 v, bool wt) { if (wt) st16_wt_e(p, v); else *(u32x4*)p = v; }
; __device__ __forceinline__ u32x4 pack8(const f32x4& v0, const f32x4& v1) { u32x4 w; w.x = cvt_pk_bf16(v0[0], v0[1]); w.y = cvt_pk_bf16(v0[2], v0[3]); w.z = cvt_pk_bf16(v1[0], v1[1]); w.w = cvt_pk_bf16(v1[2], v1[3]); return w; }
;     __device__ __forceinline__ void operator()(const f32x4 (&acc)[2][2][4][2], const Unit& u, int wr, int wc, int fr, int fq, int rowmask, const PG8_LAS unsigned char* ev) const {
;         const int pn = u.pn, row0 = u.pm * BM + wr * 64 + fr, gcol0 = pn * BM + wc * 32 + 8 * fq, oc = pn * 128 + wc * 32 + 8 * fq;
;         f32x4 k1[2][2], k2[2][2]; EPV_K(k1, k2);
;         const int rl0 = wr * 64 + fr;
; #pragma unroll
;         for (int ai = 0; ai < 2; ++ai)
; #pragma unroll
;             for (int m = 0; m < 4; ++m) { if (!((rowmask >> (ai * 4 + m)) & 1)) continue; const int row = row0 + ai * HALF + m * 16; float rA, rB; ln_row_lds(ev, rl0 + ai * HALF + m * 16, rA, rB);
;                 f32x4 v[2];
; #pragma unroll
;                 for (int n = 0; n < 2; ++n) { const f32x4 a = acc[ai][0][m][n] * rA + (k1[0][n] * rB + k2[0][n]), g = acc[ai][1][m][n] * rA + (k1[1][n] * rB + k2[1][n]);
;                     v[n] = vsilu(a) * g; }
;                 st16_sel(H + (size_t)row * 2816 + oc, pack8(v[0], v[1]), (rowmask & 0x200) != 0); }
.LBB0_1180:
	v_readlane_b32 s21, v255, 62
	s_cmp_gt_u32 s21, 2
	s_cbranch_scc1 .Ltch_done
	s_cmp_gt_u32 s31, 4
	s_cbranch_scc1 .Ltch_done
	s_lshr_b32 s1, s75, 6
	s_cmp_gt_u32 s1, 3
	s_cbranch_scc1 .Ltch_done
	s_and_b32 s0, s30, 7
	s_and_b32 s96, s53, 3
	s_lshl_b32 s96, s96, 3
	s_or_b32 s0, s0, s96
	s_lshr_b32 s96, s30, 3
	s_lshl_b32 s96, s96, 5
	s_or_b32 s0, s0, s96
	s_cmp_gt_u32 s0, 0xdf
	s_cbranch_scc1 .Ltch_done
	s_lshl_b32 s0, s0, 2
	s_or_b32 s0, s0, s1
	s_mul_i32 s1, s31, 0x380
	s_add_i32 s0, s0, s1
	s_add_i32 s21, s21, 1
	s_sub_i32 s1, s0, 0xd80
	s_movk_i32 s96, 0x88
	s_mul_i32 s84, s21, 0xb00000
	s_cmp_lt_u32 s0, 0xd80
	s_cbranch_scc0 .Ltch_go
	s_sub_i32 s1, s0, 0x800
	s_movk_i32 s96, 0x80
	s_cmp_lt_u32 s0, 0x800
	s_cbranch_scc0 .Ltch_go
	s_lshr_b32 s84, s21, 1
	s_and_b32 s85, s21, 1
	s_cmp_lt_u32 s0, 0x600
	s_cbranch_scc1 .Ltch_t0
	s_sub_i32 s1, s0, 0x600
	s_lshl_b32 s84, s84, 22
	s_cmp_eq_u32 s85, 0
	s_cselect_b32 s96, 48, 0x78
	s_branch .Ltch_go
.Ltch_t0:
	s_mov_b32 s1, s0
	s_mul_i32 s84, s84, 0xc00000
	s_cmp_eq_u32 s85, 0
	s_cselect_b32 s96, 40, 0x68
.Ltch_go:
	s_lshl_b32 s1, s1, 13
	s_add_u32 s84, s84, s1
	v_readlane_b32 s0, v250, 0
	v_readlane_b32 s1, v250, 1
	s_add_u32 s0, s0, s96
	s_addc_u32 s1, s1, 0
	s_load_dwordx2 s[0:1], s[0:1], 0x0
	v_mbcnt_lo_u32_b32 v232, -1, 0
	v_mbcnt_hi_u32_b32 v232, -1, v232
	v_lshlrev_b32_e32 v232, 7, v232
	s_waitcnt lgkmcnt(0)
	s_add_u32 s0, s0, s84
	s_addc_u32 s1, s1, 0
	global_load_dword v234, v232, s[0:1] nt
.Ltch_done:
	s_lshl_b32 s0, s31, 12
	s_and_b32 s0, s0, 0x1000
	s_add_i32 s0, s0, 0
	s_add_i32 s0, s0, 0x20400
	v_add_u32_e32 v138, s0, v175
	v_add_u32_e32 v180, s0, v176
	ds_read_b128 v[154:157], v138 offset:2048
	ds_read_b128 v[134:137], v138 offset:2064
	ds_read_b128 v[158:161], v138 offset:3072
	ds_read_b128 v[142:145], v138 offset:3088
	ds_read_b128 v[146:149], v138 offset:2560
	ds_read_b128 v[150:153], v138 offset:3584
	ds_read_b128 v[130:133], v138 offset:2576
	ds_read_b128 v[138:141], v138 offset:3600
	ds_read_b64 v[184:185], v180
	v_readlane_b32 s0, v255, 16
	v_lshl_or_b32 v182, s53, 7, v174
	v_readlane_b32 s1, v255, 17
	v_lshl_add_u32 v179, s30, 8, v0
	s_waitcnt lgkmcnt(0)
	v_pk_mul_f32 v[184:185], v[184:185], s[6:7] op_sel_hi:[1,0]
	v_ashrrev_i32_e32 v183, 31, v182
	v_fma_f32 v181, -v184, v184, v185
	v_max_f32_e32 v181, 0, v181
	v_add_f32_e32 v181, 0x3727c5ac, v181
	v_rsq_f32_e32 v186, v181
	s_movk_i32 s21, 0x1600
	s_mov_b64 s[30:31], -1
	s_andn2_b64 vcc, exec, s[10:11]
	v_mul_f32_e64 v184, v184, -v186
	v_pk_fma_f32 v[188:189], v[154:155], v[184:185], v[158:159] op_sel_hi:[1,0,1]
	v_pk_fma_f32 v[190:191], v[156:157], v[184:185], v[160:161] op_sel_hi:[1,0,1]
	v_pk_fma_f32 v[122:123], v[122:123], v[186:187], v[188:189] op_sel_hi:[1,0,1]
	v_pk_fma_f32 v[124:125], v[124:125], v[186:187], v[190:191] op_sel_hi:[1,0,1]
	v_mul_f32_e32 v181, 0xbfb8aa3b, v122
	v_pk_fma_f32 v[188:189], v[148:149], v[184:185], v[152:153] op_sel_hi:[1,0,1]
	v_pk_fma_f32 v[190:191], v[146:147], v[184:185], v[150:151] op_sel_hi:[1,0,1]
	v_exp_f32_e32 v181, v181
	v_mul_f32_e32 v185, 0xbfb8aa3b, v123
	v_pk_fma_f32 v[126:127], v[126:127], v[186:187], v[190:191] op_sel_hi:[1,0,1]
	v_pk_fma_f32 v[128:129], v[128:129], v[186:187], v[188:189] op_sel_hi:[1,0,1]
	v_exp_f32_e32 v185, v185
	v_mul_f32_e32 v187, 0xbfb8aa3b, v124
	v_exp_f32_e32 v187, v187
	v_mul_f32_e32 v188, 0xbfb8aa3b, v125
	v_exp_f32_e32 v191, v188
	v_add_f32_e32 v181, 1.0, v181
	v_rcp_f32_e32 v188, v181
	v_add_f32_e32 v181, 1.0, v185
	v_rcp_f32_e32 v189, v181
	v_add_f32_e32 v181, 1.0, v187
	v_rcp_f32_e32 v190, v181
	v_add_f32_e32 v181, 1.0, v191
	v_rcp_f32_e32 v191, v181
	v_pk_mul_f32 v[122:123], v[122:123], v[188:189]
	s_mov_b32 s96, 0x11000
	v_pk_mul_f32 v[122:123], v[126:127], v[122:123]
	v_pk_mul_f32 v[124:125], v[124:125], v[190:191]
	v_pk_fma_f32 v[126:127], v[134:135], v[184:185], v[142:143] op_sel_hi:[1,0,1]
	v_pk_mul_f32 v[124:125], v[128:129], v[124:125]
	v_pk_fma_f32 v[128:129], v[136:137], v[184:185], v[144:145] op_sel_hi:[1,0,1]
	v_pk_fma_f32 v[114:115], v[114:115], v[186:187], v[126:127] op_sel_hi:[1,0,1]
	v_pk_fma_f32 v[116:117], v[116:117], v[186:187], v[128:129] op_sel_hi:[1,0,1]
	v_pk_fma_f32 v[126:127], v[132:133], v[184:185], v[140:141] op_sel_hi:[1,0,1]
	v_pk_fma_f32 v[128:129], v[130:131], v[184:185], v[138:139] op_sel_hi:[1,0,1]
	v_pk_fma_f32 v[120:121], v[120:121], v[186:187], v[126:127] op_sel_hi:[1,0,1]
	v_pk_fma_f32 v[118:119], v[118:119], v[186:187], v[128:129] op_sel_hi:[1,0,1]
	v_mul_f32_e32 v126, 0xbfb8aa3b, v114
	v_mul_f32_e32 v127, 0xbfb8aa3b, v115
	v_mul_f32_e32 v128, 0xbfb8aa3b, v116
	v_mul_f32_e32 v129, 0xbfb8aa3b, v117
	v_exp_f32_e32 v126, v126
	v_exp_f32_e32 v127, v127
	v_exp_f32_e32 v128, v128
	v_exp_f32_e32 v129, v129
	v_add_f32_e32 v126, 1.0, v126
	v_add_f32_e32 v127, 1.0, v127
	v_add_f32_e32 v128, 1.0, v128
	v_add_f32_e32 v129, 1.0, v129
	v_rcp_f32_e32 v126, v126
	v_rcp_f32_e32 v127, v127
	v_rcp_f32_e32 v128, v128
	v_rcp_f32_e32 v129, v129
	s_mov_b64 s[84:85], 0x100
	v_pk_mul_f32 v[114:115], v[114:115], v[126:127]
	v_pk_mul_f32 v[116:117], v[116:117], v[128:129]
	s_nop 0
	v_pk_mul_f32 v[126:127], v[120:121], v[116:117]
	v_pk_mul_f32 v[120:121], v[118:119], v[114:115]
	v_mov_b64_e32 v[114:115], s[0:1]
	v_mad_i64_i32 v[118:119], s[0:1], v179, s21, v[114:115]
	v_lshlrev_b64 v[116:117], 1, v[182:183]
	v_lshl_add_u64 v[128:129], v[118:119], 0, v[116:117]
	v_cvt_pk_bf16_f32 v118, v122, v123
	v_cvt_pk_bf16_f32 v119, v124, v125
	v_cvt_pk_bf16_f32 v120, v120, v121
	v_cvt_pk_bf16_f32 v121, v126, v127
	global_store_dwordx4 v[128:129], v[118:121], off
	ds_read_b64 v[118:119], v180 offset:128
	s_waitcnt lgkmcnt(0)
; __device__ __forceinline__ f32x4 vsilu(const f32x4& x) { return x * vsig(x); }
; __device__ __forceinline__ void st16_sel(void* p, u32x4 v, bool wt) { if (wt) st16_wt_e(p, v); else *(u32x4*)p = v; }
; __device__ __forceinline__ u32x4 pack8(const f32x4& v0, const f32x4& v1) { u32x4 w; w.x = cvt_pk_bf16(v0[0], v0[1]); w.y = cvt_pk_bf16(v0[2], v0[3]); w.z = cvt_pk_bf16(v1[0], v1[1]); w.w = cvt_pk_bf16(v1[2], v1[3]); return w; }
;     __device__ __forceinline__ void operator()(const f32x4 (&acc)[2][2][4][2], const Unit& u, int wr, int wc, int fr, int fq, int rowmask, const PG8_LAS unsigned char* ev) const {
;     ...
;             for (int m = 0; m < 4; ++m) { if (!((rowmask >> (ai * 4 + m)) & 1)) continue; const int row = row0 + ai * HALF + m * 16; float rA, rB; ln_row_lds(ev, rl0 + ai * HALF + m * 16, rA, rB);
;                 f32x4 v[2];
; #pragma unroll
;                 for (int n = 0; n < 2; ++n) { const f32x4 a = acc[ai][0][m][n] * rA + (k1[0][n] * rB + k2[0][n]), g = acc[ai][1][m][n] * rA + (k1[1][n] * rB + k2[1][n]);
;                     v[n] = vsilu(a) * g; }
;                 st16_sel(H + (size_t)row * 2816 + oc, pack8(v[0], v[1]), (rowmask & 0x200) != 0); }
	v_pk_mul_f32 v[118:119], v[118:119], s[6:7] op_sel_hi:[1,0]
	s_nop 0
	v_fma_f32 v119, -v118, v118, v119
	v_max_f32_e32 v119, 0, v119
	v_add_f32_e32 v119, 0x3727c5ac, v119
	v_rsq_f32_e32 v120, v119
	s_nop 0
	v_mul_f32_e64 v118, v118, -v120
	v_pk_fma_f32 v[122:123], v[154:155], v[118:119], v[158:159] op_sel_hi:[1,0,1]
	v_pk_fma_f32 v[124:125], v[156:157], v[118:119], v[160:161] op_sel_hi:[1,0,1]
	v_pk_fma_f32 v[106:107], v[106:107], v[120:121], v[122:123] op_sel_hi:[1,0,1]
	v_pk_fma_f32 v[108:109], v[108:109], v[120:121], v[124:125] op_sel_hi:[1,0,1]
	v_pk_fma_f32 v[122:123], v[148:149], v[118:119], v[152:153] op_sel_hi:[1,0,1]
	v_pk_fma_f32 v[124:125], v[146:147], v[118:119], v[150:151] op_sel_hi:[1,0,1]
	v_mul_f32_e32 v119, 0xbfb8aa3b, v106
	v_pk_fma_f32 v[110:111], v[110:111], v[120:121], v[124:125] op_sel_hi:[1,0,1]
	v_pk_fma_f32 v[112:113], v[112:113], v[120:121], v[122:123] op_sel_hi:[1,0,1]
	v_exp_f32_e32 v119, v119
	v_mul_f32_e32 v121, 0xbfb8aa3b, v107
	v_exp_f32_e32 v121, v121
	v_mul_f32_e32 v122, 0xbfb8aa3b, v108
	v_exp_f32_e32 v124, v122
	v_mul_f32_e32 v122, 0xbfb8aa3b, v109
	v_exp_f32_e32 v125, v122
	v_add_f32_e32 v119, 1.0, v119
	v_rcp_f32_e32 v122, v119
	v_add_f32_e32 v119, 1.0, v121
	v_rcp_f32_e32 v123, v119
	v_add_f32_e32 v119, 1.0, v124
	v_rcp_f32_e32 v124, v119
	v_add_f32_e32 v119, 1.0, v125
	v_rcp_f32_e32 v125, v119
	v_pk_mul_f32 v[106:107], v[106:107], v[122:123]
	v_pk_mul_f32 v[108:109], v[108:109], v[124:125]
	s_nop 0
	v_pk_mul_f32 v[108:109], v[112:113], v[108:109]
	v_pk_mul_f32 v[106:107], v[110:111], v[106:107]
	v_pk_fma_f32 v[110:111], v[134:135], v[118:119], v[142:143] op_sel_hi:[1,0,1]
	v_pk_fma_f32 v[112:113], v[136:137], v[118:119], v[144:145] op_sel_hi:[1,0,1]
	v_pk_fma_f32 v[98:99], v[98:99], v[120:121], v[110:111] op_sel_hi:[1,0,1]
	v_pk_fma_f32 v[100:101], v[100:101], v[120:121], v[112:113] op_sel_hi:[1,0,1]
	v_pk_fma_f32 v[110:111], v[132:133], v[118:119], v[140:141] op_sel_hi:[1,0,1]
	v_pk_fma_f32 v[112:113], v[130:131], v[118:119], v[138:139] op_sel_hi:[1,0,1]
	v_pk_fma_f32 v[104:105], v[104:105], v[120:121], v[110:111] op_sel_hi:[1,0,1]
	v_pk_fma_f32 v[102:103], v[102:103], v[120:121], v[112:113] op_sel_hi:[1,0,1]
	v_mul_f32_e32 v110, 0xbfb8aa3b, v98
	v_mul_f32_e32 v111, 0xbfb8aa3b, v99
	v_mul_f32_e32 v112, 0xbfb8aa3b, v100
	v_mul_f32_e32 v113, 0xbfb8aa3b, v101
	v_exp_f32_e32 v110, v110
	v_exp_f32_e32 v111, v111
	v_exp_f32_e32 v112, v112
	v_exp_f32_e32 v113, v113
	v_add_f32_e32 v110, 1.0, v110
	v_add_f32_e32 v111, 1.0, v111
	v_add_f32_e32 v112, 1.0, v112
	v_add_f32_e32 v113, 1.0, v113
	v_rcp_f32_e32 v110, v110
	v_rcp_f32_e32 v111, v111
	v_rcp_f32_e32 v112, v112
	v_rcp_f32_e32 v113, v113
	v_pk_mul_f32 v[98:99], v[98:99], v[110:111]
	v_pk_mul_f32 v[100:101], v[100:101], v[112:113]
	s_nop 0
	v_pk_mul_f32 v[104:105], v[104:105], v[100:101]
	v_pk_mul_f32 v[100:101], v[102:103], v[98:99]
	v_or_b32_e32 v98, 16, v179
	v_mad_i64_i32 v[98:99], s[0:1], v98, s21, v[114:115]
	v_lshl_add_u64 v[102:103], v[98:99], 0, v[116:117]
	v_cvt_pk_bf16_f32 v98, v106, v107
	v_cvt_pk_bf16_f32 v99, v108, v109
	v_cvt_pk_bf16_f32 v100, v100, v101
	v_cvt_pk_bf16_f32 v101, v104, v105
	global_store_dwordx4 v[102:103], v[98:101], off
	ds_read_b64 v[98:99], v180 offset:256
	s_waitcnt lgkmcnt(0)
	v_pk_mul_f32 v[98:99], v[98:99], s[6:7] op_sel_hi:[1,0]
	s_nop 0
	v_fma_f32 v99, -v98, v98, v99
	v_max_f32_e32 v99, 0, v99
	v_add_f32_e32 v99, 0x3727c5ac, v99
	v_rsq_f32_e32 v100, v99
	s_nop 0
	v_mul_f32_e64 v98, v98, -v100
	v_pk_fma_f32 v[102:103], v[154:155], v[98:99], v[158:159] op_sel_hi:[1,0,1]
	v_pk_fma_f32 v[104:105], v[156:157], v[98:99], v[160:161] op_sel_hi:[1,0,1]
	v_pk_fma_f32 v[90:91], v[90:91], v[100:101], v[102:103] op_sel_hi:[1,0,1]
	v_pk_fma_f32 v[92:93], v[92:93], v[100:101], v[104:105] op_sel_hi:[1,0,1]
	v_pk_fma_f32 v[102:103], v[148:149], v[98:99], v[152:153] op_sel_hi:[1,0,1]
	v_pk_fma_f32 v[104:105], v[146:147], v[98:99], v[150:151] op_sel_hi:[1,0,1]
	v_mul_f32_e32 v99, 0xbfb8aa3b, v90
	v_pk_fma_f32 v[94:95], v[94:95], v[100:101], v[104:105] op_sel_hi:[1,0,1]
	v_pk_fma_f32 v[96:97], v[96:97], v[100:101], v[102:103] op_sel_hi:[1,0,1]
	v_exp_f32_e32 v99, v99
	v_mul_f32_e32 v101, 0xbfb8aa3b, v91
	v_exp_f32_e32 v101, v101
	v_mul_f32_e32 v102, 0xbfb8aa3b, v92
	v_exp_f32_e32 v104, v102
	v_mul_f32_e32 v102, 0xbfb8aa3b, v93
	v_exp_f32_e32 v105, v102
	v_add_f32_e32 v99, 1.0, v99
	v_rcp_f32_e32 v102, v99
	v_add_f32_e32 v99, 1.0, v101
	v_rcp_f32_e32 v103, v99
	v_add_f32_e32 v99, 1.0, v104
	v_rcp_f32_e32 v104, v99
	v_add_f32_e32 v99, 1.0, v105
	v_rcp_f32_e32 v105, v99
	v_pk_mul_f32 v[90:91], v[90:91], v[102:103]
	v_pk_mul_f32 v[92:93], v[92:93], v[104:105]
	s_nop 0
	v_pk_mul_f32 v[92:93], v[96:97], v[92:93]
	v_pk_mul_f32 v[90:91], v[94:95], v[90:91]
	v_pk_fma_f32 v[94:95], v[134:135], v[98:99], v[142:143] op_sel_hi:[1,0,1]
	v_pk_fma_f32 v[96:97], v[136:137], v[98:99], v[144:145] op_sel_hi:[1,0,1]
	v_pk_fma_f32 v[82:83], v[82:83], v[100:101], v[94:95] op_sel_hi:[1,0,1]
	v_pk_fma_f32 v[84:85], v[84:85], v[100:101], v[96:97] op_sel_hi:[1,0,1]
	v_pk_fma_f32 v[94:95], v[132:133], v[98:99], v[140:141] op_sel_hi:[1,0,1]
	v_pk_fma_f32 v[96:97], v[130:131], v[98:99], v[138:139] op_sel_hi:[1,0,1]
	v_pk_fma_f32 v[88:89], v[88:89], v[100:101], v[94:95] op_sel_hi:[1,0,1]
	v_pk_fma_f32 v[86:87], v[86:87], v[100:101], v[96:97] op_sel_hi:[1,0,1]
	v_mul_f32_e32 v94, 0xbfb8aa3b, v82
	v_mul_f32_e32 v95, 0xbfb8aa3b, v83
	v_mul_f32_e32 v96, 0xbfb8aa3b, v84
	v_mul_f32_e32 v97, 0xbfb8aa3b, v85
	v_exp_f32_e32 v94, v94
	v_exp_f32_e32 v95, v95
	v_exp_f32_e32 v96, v96
	v_exp_f32_e32 v97, v97
	v_add_f32_e32 v94, 1.0, v94
	v_add_f32_e32 v95, 1.0, v95
	v_add_f32_e32 v96, 1.0, v96
	v_add_f32_e32 v97, 1.0, v97
	v_rcp_f32_e32 v94, v94
	v_rcp_f32_e32 v95, v95
	v_rcp_f32_e32 v96, v96
	v_rcp_f32_e32 v97, v97
	v_pk_mul_f32 v[82:83], v[82:83], v[94:95]
	v_pk_mul_f32 v[84:85], v[84:85], v[96:97]
	s_nop 0
	v_pk_mul_f32 v[88:89], v[88:89], v[84:85]
	v_pk_mul_f32 v[84:85], v[86:87], v[82:83]
	v_or_b32_e32 v82, 32, v179
	v_mad_i64_i32 v[82:83], s[0:1], v82, s21, v[114:115]
	v_lshl_add_u64 v[86:87], v[82:83], 0, v[116:117]
	v_cvt_pk_bf16_f32 v82, v90, v91
	v_cvt_pk_bf16_f32 v83, v92, v93
	v_cvt_pk_bf16_f32 v84, v84, v85
	v_cvt_pk_bf16_f32 v85, v88, v89
	global_store_dwordx4 v[86:87], v[82:85], off
	ds_read_b64 v[82:83], v180 offset:384
	s_waitcnt lgkmcnt(0)
; __device__ __forceinline__ f32x4 vsilu(const f32x4& x) { return x * vsig(x); }
; __device__ __forceinline__ void st16_sel(void* p, u32x4 v, bool wt) { if (wt) st16_wt_e(p, v); else *(u32x4*)p = v; }
; __device__ __forceinline__ u32x4 pack8(const f32x4& v0, const f32x4& v1) { u32x4 w; w.x = cvt_pk_bf16(v0[0], v0[1]); w.y = cvt_pk_bf16(v0[2], v0[3]); w.z = cvt_pk_bf16(v1[0], v1[1]); w.w = cvt_pk_bf16(v1[2], v1[3]); return w; }
;     __device__ __forceinline__ void operator()(const f32x4 (&acc)[2][2][4][2], const Unit& u, int wr, int wc, int fr, int fq, int rowmask, const PG8_LAS unsigned char* ev) const {
;     ...
;             for (int m = 0; m < 4; ++m) { if (!((rowmask >> (ai * 4 + m)) & 1)) continue; const int row = row0 + ai * HALF + m * 16; float rA, rB; ln_row_lds(ev, rl0 + ai * HALF + m * 16, rA, rB);
;                 f32x4 v[2];
; #pragma unroll
;                 for (int n = 0; n < 2; ++n) { const f32x4 a = acc[ai][0][m][n] * rA + (k1[0][n] * rB + k2[0][n]), g = acc[ai][1][m][n] * rA + (k1[1][n] * rB + k2[1][n]);
;                     v[n] = vsilu(a) * g; }
;                 st16_sel(H + (size_t)row * 2816 + oc, pack8(v[0], v[1]), (rowmask & 0x200) != 0); }
	v_pk_mul_f32 v[82:83], v[82:83], s[6:7] op_sel_hi:[1,0]
	s_nop 0
	v_fma_f32 v83, -v82, v82, v83
	v_max_f32_e32 v83, 0, v83
	v_add_f32_e32 v83, 0x3727c5ac, v83
	v_rsq_f32_e32 v84, v83
	s_nop 0
	v_mul_f32_e64 v82, v82, -v84
	v_pk_fma_f32 v[86:87], v[154:155], v[82:83], v[158:159] op_sel_hi:[1,0,1]
	v_pk_fma_f32 v[88:89], v[156:157], v[82:83], v[160:161] op_sel_hi:[1,0,1]
	v_pk_fma_f32 v[74:75], v[74:75], v[84:85], v[86:87] op_sel_hi:[1,0,1]
	v_pk_fma_f32 v[76:77], v[76:77], v[84:85], v[88:89] op_sel_hi:[1,0,1]
	v_pk_fma_f32 v[86:87], v[148:149], v[82:83], v[152:153] op_sel_hi:[1,0,1]
	v_pk_fma_f32 v[88:89], v[146:147], v[82:83], v[150:151] op_sel_hi:[1,0,1]
	v_mul_f32_e32 v83, 0xbfb8aa3b, v74
	v_pk_fma_f32 v[78:79], v[78:79], v[84:85], v[88:89] op_sel_hi:[1,0,1]
	v_pk_fma_f32 v[80:81], v[80:81], v[84:85], v[86:87] op_sel_hi:[1,0,1]
	v_exp_f32_e32 v83, v83
	v_mul_f32_e32 v85, 0xbfb8aa3b, v75
	v_exp_f32_e32 v85, v85
	v_mul_f32_e32 v86, 0xbfb8aa3b, v76
	v_exp_f32_e32 v88, v86
	v_mul_f32_e32 v86, 0xbfb8aa3b, v77
	v_exp_f32_e32 v89, v86
	v_add_f32_e32 v83, 1.0, v83
	v_rcp_f32_e32 v86, v83
	v_add_f32_e32 v83, 1.0, v85
	v_rcp_f32_e32 v87, v83
	v_add_f32_e32 v83, 1.0, v88
	v_rcp_f32_e32 v88, v83
	v_add_f32_e32 v83, 1.0, v89
	v_rcp_f32_e32 v89, v83
	v_pk_mul_f32 v[74:75], v[74:75], v[86:87]
	v_pk_mul_f32 v[76:77], v[76:77], v[88:89]
	s_nop 0
	v_pk_mul_f32 v[76:77], v[80:81], v[76:77]
	v_pk_mul_f32 v[74:75], v[78:79], v[74:75]
	v_pk_fma_f32 v[78:79], v[134:135], v[82:83], v[142:143] op_sel_hi:[1,0,1]
	v_pk_fma_f32 v[80:81], v[136:137], v[82:83], v[144:145] op_sel_hi:[1,0,1]
	v_pk_fma_f32 v[66:67], v[66:67], v[84:85], v[78:79] op_sel_hi:[1,0,1]
	v_pk_fma_f32 v[68:69], v[68:69], v[84:85], v[80:81] op_sel_hi:[1,0,1]
	v_pk_fma_f32 v[78:79], v[132:133], v[82:83], v[140:141] op_sel_hi:[1,0,1]
	v_pk_fma_f32 v[80:81], v[130:131], v[82:83], v[138:139] op_sel_hi:[1,0,1]
	v_pk_fma_f32 v[72:73], v[72:73], v[84:85], v[78:79] op_sel_hi:[1,0,1]
	v_pk_fma_f32 v[70:71], v[70:71], v[84:85], v[80:81] op_sel_hi:[1,0,1]
	v_mul_f32_e32 v78, 0xbfb8aa3b, v66
	v_mul_f32_e32 v79, 0xbfb8aa3b, v67
	v_mul_f32_e32 v80, 0xbfb8aa3b, v68
	v_mul_f32_e32 v81, 0xbfb8aa3b, v69
	v_exp_f32_e32 v78, v78
	v_exp_f32_e32 v79, v79
	v_exp_f32_e32 v80, v80
	v_exp_f32_e32 v81, v81
	v_add_f32_e32 v78, 1.0, v78
	v_add_f32_e32 v79, 1.0, v79
	v_add_f32_e32 v80, 1.0, v80
	v_add_f32_e32 v81, 1.0, v81
	v_rcp_f32_e32 v78, v78
	v_rcp_f32_e32 v79, v79
	v_rcp_f32_e32 v80, v80
	v_rcp_f32_e32 v81, v81
	v_pk_mul_f32 v[66:67], v[66:67], v[78:79]
	v_pk_mul_f32 v[68:69], v[68:69], v[80:81]
	s_nop 0
	v_pk_mul_f32 v[72:73], v[72:73], v[68:69]
	v_pk_mul_f32 v[68:69], v[70:71], v[66:67]
	v_or_b32_e32 v66, 48, v179
	v_mad_i64_i32 v[66:67], s[0:1], v66, s21, v[114:115]
	v_lshl_add_u64 v[70:71], v[66:67], 0, v[116:117]
	v_cvt_pk_bf16_f32 v66, v74, v75
	v_cvt_pk_bf16_f32 v67, v76, v77
	v_cvt_pk_bf16_f32 v68, v68, v69
	v_cvt_pk_bf16_f32 v69, v72, v73
	global_store_dwordx4 v[70:71], v[66:69], off
	ds_read_b64 v[66:67], v180 offset:1024
	s_nop 0
	v_add_u32_e32 v69, 0x80, v179
	s_waitcnt lgkmcnt(0)
	v_pk_mul_f32 v[66:67], v[66:67], s[6:7] op_sel_hi:[1,0]
	s_nop 0
	v_fma_f32 v67, -v66, v66, v67
	v_max_f32_e32 v67, 0, v67
	v_add_f32_e32 v67, 0x3727c5ac, v67
	v_rsq_f32_e32 v68, v67
	s_nop 0
	v_mul_f32_e64 v66, v66, -v68
	v_pk_fma_f32 v[70:71], v[154:155], v[66:67], v[158:159] op_sel_hi:[1,0,1]
	v_pk_fma_f32 v[72:73], v[156:157], v[66:67], v[160:161] op_sel_hi:[1,0,1]
	v_pk_fma_f32 v[58:59], v[58:59], v[68:69], v[70:71] op_sel_hi:[1,0,1]
	v_pk_fma_f32 v[60:61], v[60:61], v[68:69], v[72:73] op_sel_hi:[1,0,1]
	v_pk_fma_f32 v[70:71], v[148:149], v[66:67], v[152:153] op_sel_hi:[1,0,1]
	v_pk_fma_f32 v[72:73], v[146:147], v[66:67], v[150:151] op_sel_hi:[1,0,1]
	v_mul_f32_e32 v67, 0xbfb8aa3b, v58
	v_pk_fma_f32 v[64:65], v[64:65], v[68:69], v[70:71] op_sel_hi:[1,0,1]
	v_exp_f32_e32 v67, v67
	v_mul_f32_e32 v70, 0xbfb8aa3b, v59
	v_exp_f32_e32 v71, v70
	v_mul_f32_e32 v70, 0xbfb8aa3b, v60
	v_pk_fma_f32 v[62:63], v[62:63], v[68:69], v[72:73] op_sel_hi:[1,0,1]
	v_exp_f32_e32 v72, v70
	v_mul_f32_e32 v70, 0xbfb8aa3b, v61
	v_exp_f32_e32 v73, v70
	v_add_f32_e32 v67, 1.0, v67
	v_rcp_f32_e32 v70, v67
	v_add_f32_e32 v67, 1.0, v71
	v_rcp_f32_e32 v71, v67
	v_add_f32_e32 v67, 1.0, v72
	v_rcp_f32_e32 v72, v67
	v_add_f32_e32 v67, 1.0, v73
	v_rcp_f32_e32 v73, v67
	v_pk_mul_f32 v[58:59], v[58:59], v[70:71]
	v_pk_mul_f32 v[60:61], v[60:61], v[72:73]
	s_nop 0
	v_pk_mul_f32 v[60:61], v[64:65], v[60:61]
	v_pk_mul_f32 v[58:59], v[62:63], v[58:59]
	v_pk_fma_f32 v[62:63], v[134:135], v[66:67], v[142:143] op_sel_hi:[1,0,1]
	v_pk_fma_f32 v[64:65], v[136:137], v[66:67], v[144:145] op_sel_hi:[1,0,1]
	v_pk_fma_f32 v[50:51], v[50:51], v[68:69], v[62:63] op_sel_hi:[1,0,1]
	v_pk_fma_f32 v[52:53], v[52:53], v[68:69], v[64:65] op_sel_hi:[1,0,1]
	v_pk_fma_f32 v[62:63], v[132:133], v[66:67], v[140:141] op_sel_hi:[1,0,1]
	v_pk_fma_f32 v[64:65], v[130:131], v[66:67], v[138:139] op_sel_hi:[1,0,1]
	v_pk_fma_f32 v[56:57], v[56:57], v[68:69], v[62:63] op_sel_hi:[1,0,1]
	v_pk_fma_f32 v[54:55], v[54:55], v[68:69], v[64:65] op_sel_hi:[1,0,1]
	v_mul_f32_e32 v62, 0xbfb8aa3b, v50
	v_mul_f32_e32 v63, 0xbfb8aa3b, v51
	v_mul_f32_e32 v64, 0xbfb8aa3b, v52
	v_mul_f32_e32 v65, 0xbfb8aa3b, v53
	v_exp_f32_e32 v62, v62
	v_exp_f32_e32 v63, v63
	v_exp_f32_e32 v64, v64
	v_exp_f32_e32 v65, v65
	v_add_f32_e32 v62, 1.0, v62
	v_add_f32_e32 v63, 1.0, v63
	v_add_f32_e32 v64, 1.0, v64
	v_add_f32_e32 v65, 1.0, v65
	v_rcp_f32_e32 v62, v62
	v_rcp_f32_e32 v63, v63
	v_rcp_f32_e32 v64, v64
	v_rcp_f32_e32 v65, v65
	v_pk_mul_f32 v[50:51], v[50:51], v[62:63]
	v_pk_mul_f32 v[52:53], v[52:53], v[64:65]
	s_nop 0
	v_pk_mul_f32 v[56:57], v[56:57], v[52:53]
	v_pk_mul_f32 v[52:53], v[54:55], v[50:51]
	v_mad_i64_i32 v[50:51], s[0:1], v69, s21, v[114:115]
	v_lshl_add_u64 v[54:55], v[50:51], 0, v[116:117]
	v_cvt_pk_bf16_f32 v50, v58, v59
	v_cvt_pk_bf16_f32 v51, v60, v61
	v_cvt_pk_bf16_f32 v52, v52, v53
	v_cvt_pk_bf16_f32 v53, v56, v57
	global_store_dwordx4 v[54:55], v[50:53], off
	ds_read_b64 v[50:51], v180 offset:1152
	s_waitcnt lgkmcnt(0)
; __device__ __forceinline__ f32x4 vsilu(const f32x4& x) { return x * vsig(x); }
; __device__ __forceinline__ void st16_sel(void* p, u32x4 v, bool wt) { if (wt) st16_wt_e(p, v); else *(u32x4*)p = v; }
; __device__ __forceinline__ u32x4 pack8(const f32x4& v0, const f32x4& v1) { u32x4 w; w.x = cvt_pk_bf16(v0[0], v0[1]); w.y = cvt_pk_bf16(v0[2], v0[3]); w.z = cvt_pk_bf16(v1[0], v1[1]); w.w = cvt_pk_bf16(v1[2], v1[3]); return w; }
;     __device__ __forceinline__ void operator()(const f32x4 (&acc)[2][2][4][2], const Unit& u, int wr, int wc, int fr, int fq, int rowmask, const PG8_LAS unsigned char* ev) const {
;     ...
;             for (int m = 0; m < 4; ++m) { if (!((rowmask >> (ai * 4 + m)) & 1)) continue; const int row = row0 + ai * HALF + m * 16; float rA, rB; ln_row_lds(ev, rl0 + ai * HALF + m * 16, rA, rB);
;                 f32x4 v[2];
; #pragma unroll
;                 for (int n = 0; n < 2; ++n) { const f32x4 a = acc[ai][0][m][n] * rA + (k1[0][n] * rB + k2[0][n]), g = acc[ai][1][m][n] * rA + (k1[1][n] * rB + k2[1][n]);
;                     v[n] = vsilu(a) * g; }
;                 st16_sel(H + (size_t)row * 2816 + oc, pack8(v[0], v[1]), (rowmask & 0x200) != 0); }
	v_pk_mul_f32 v[50:51], v[50:51], s[6:7] op_sel_hi:[1,0]
	s_nop 0
	v_fma_f32 v51, -v50, v50, v51
	v_max_f32_e32 v51, 0, v51
	v_add_f32_e32 v51, 0x3727c5ac, v51
	v_rsq_f32_e32 v52, v51
	s_nop 0
	v_mul_f32_e64 v50, v50, -v52
	v_pk_fma_f32 v[54:55], v[154:155], v[50:51], v[158:159] op_sel_hi:[1,0,1]
	v_pk_fma_f32 v[56:57], v[156:157], v[50:51], v[160:161] op_sel_hi:[1,0,1]
	v_pk_fma_f32 v[42:43], v[42:43], v[52:53], v[54:55] op_sel_hi:[1,0,1]
	v_pk_fma_f32 v[44:45], v[44:45], v[52:53], v[56:57] op_sel_hi:[1,0,1]
	v_pk_fma_f32 v[54:55], v[148:149], v[50:51], v[152:153] op_sel_hi:[1,0,1]
	v_pk_fma_f32 v[56:57], v[146:147], v[50:51], v[150:151] op_sel_hi:[1,0,1]
	v_mul_f32_e32 v51, 0xbfb8aa3b, v42
	v_pk_fma_f32 v[46:47], v[46:47], v[52:53], v[56:57] op_sel_hi:[1,0,1]
	v_pk_fma_f32 v[48:49], v[48:49], v[52:53], v[54:55] op_sel_hi:[1,0,1]
	v_exp_f32_e32 v51, v51
	v_mul_f32_e32 v53, 0xbfb8aa3b, v43
	v_exp_f32_e32 v53, v53
	v_mul_f32_e32 v54, 0xbfb8aa3b, v44
	v_exp_f32_e32 v56, v54
	v_mul_f32_e32 v54, 0xbfb8aa3b, v45
	v_exp_f32_e32 v57, v54
	v_add_f32_e32 v51, 1.0, v51
	v_rcp_f32_e32 v54, v51
	v_add_f32_e32 v51, 1.0, v53
	v_rcp_f32_e32 v55, v51
	v_add_f32_e32 v51, 1.0, v56
	v_rcp_f32_e32 v56, v51
	v_add_f32_e32 v51, 1.0, v57
	v_rcp_f32_e32 v57, v51
	v_pk_mul_f32 v[42:43], v[42:43], v[54:55]
	v_pk_mul_f32 v[44:45], v[44:45], v[56:57]
	s_nop 0
	v_pk_mul_f32 v[44:45], v[48:49], v[44:45]
	v_pk_mul_f32 v[42:43], v[46:47], v[42:43]
	v_pk_fma_f32 v[46:47], v[134:135], v[50:51], v[142:143] op_sel_hi:[1,0,1]
	v_pk_fma_f32 v[48:49], v[136:137], v[50:51], v[144:145] op_sel_hi:[1,0,1]
	v_pk_fma_f32 v[34:35], v[34:35], v[52:53], v[46:47] op_sel_hi:[1,0,1]
	v_pk_fma_f32 v[36:37], v[36:37], v[52:53], v[48:49] op_sel_hi:[1,0,1]
	v_pk_fma_f32 v[46:47], v[132:133], v[50:51], v[140:141] op_sel_hi:[1,0,1]
	v_pk_fma_f32 v[48:49], v[130:131], v[50:51], v[138:139] op_sel_hi:[1,0,1]
	v_pk_fma_f32 v[40:41], v[40:41], v[52:53], v[46:47] op_sel_hi:[1,0,1]
	v_pk_fma_f32 v[38:39], v[38:39], v[52:53], v[48:49] op_sel_hi:[1,0,1]
	v_mul_f32_e32 v46, 0xbfb8aa3b, v34
	v_mul_f32_e32 v47, 0xbfb8aa3b, v35
	v_mul_f32_e32 v48, 0xbfb8aa3b, v36
	v_mul_f32_e32 v49, 0xbfb8aa3b, v37
	v_exp_f32_e32 v46, v46
	v_exp_f32_e32 v47, v47
	v_exp_f32_e32 v48, v48
	v_exp_f32_e32 v49, v49
	v_add_f32_e32 v46, 1.0, v46
	v_add_f32_e32 v47, 1.0, v47
	v_add_f32_e32 v48, 1.0, v48
	v_add_f32_e32 v49, 1.0, v49
	v_rcp_f32_e32 v46, v46
	v_rcp_f32_e32 v47, v47
	v_rcp_f32_e32 v48, v48
	v_rcp_f32_e32 v49, v49
	v_pk_mul_f32 v[34:35], v[34:35], v[46:47]
	v_pk_mul_f32 v[36:37], v[36:37], v[48:49]
	s_nop 0
	v_pk_mul_f32 v[40:41], v[40:41], v[36:37]
	v_pk_mul_f32 v[36:37], v[38:39], v[34:35]
	v_add_u32_e32 v34, 0x90, v179
	v_mad_i64_i32 v[34:35], s[0:1], v34, s21, v[114:115]
	v_lshl_add_u64 v[38:39], v[34:35], 0, v[116:117]
	v_cvt_pk_bf16_f32 v34, v42, v43
	v_cvt_pk_bf16_f32 v35, v44, v45
	v_cvt_pk_bf16_f32 v36, v36, v37
	v_cvt_pk_bf16_f32 v37, v40, v41
	global_store_dwordx4 v[38:39], v[34:37], off
	ds_read_b64 v[34:35], v180 offset:1280
	s_waitcnt lgkmcnt(0)
	v_pk_mul_f32 v[34:35], v[34:35], s[6:7] op_sel_hi:[1,0]
	s_nop 0
	v_fma_f32 v35, -v34, v34, v35
	v_max_f32_e32 v35, 0, v35
	v_add_f32_e32 v35, 0x3727c5ac, v35
	v_rsq_f32_e32 v36, v35
	s_nop 0
	v_mul_f32_e64 v34, v34, -v36
	v_pk_fma_f32 v[38:39], v[154:155], v[34:35], v[158:159] op_sel_hi:[1,0,1]
	v_pk_fma_f32 v[40:41], v[156:157], v[34:35], v[160:161] op_sel_hi:[1,0,1]
	v_pk_fma_f32 v[26:27], v[26:27], v[36:37], v[38:39] op_sel_hi:[1,0,1]
	v_pk_fma_f32 v[28:29], v[28:29], v[36:37], v[40:41] op_sel_hi:[1,0,1]
	v_pk_fma_f32 v[38:39], v[148:149], v[34:35], v[152:153] op_sel_hi:[1,0,1]
	v_pk_fma_f32 v[40:41], v[146:147], v[34:35], v[150:151] op_sel_hi:[1,0,1]
	v_mul_f32_e32 v35, 0xbfb8aa3b, v26
	v_pk_fma_f32 v[30:31], v[30:31], v[36:37], v[40:41] op_sel_hi:[1,0,1]
	v_pk_fma_f32 v[32:33], v[32:33], v[36:37], v[38:39] op_sel_hi:[1,0,1]
	v_exp_f32_e32 v35, v35
	v_mul_f32_e32 v37, 0xbfb8aa3b, v27
	v_exp_f32_e32 v37, v37
	v_mul_f32_e32 v38, 0xbfb8aa3b, v28
	v_exp_f32_e32 v40, v38
	v_mul_f32_e32 v38, 0xbfb8aa3b, v29
	v_exp_f32_e32 v41, v38
	v_add_f32_e32 v35, 1.0, v35
	v_rcp_f32_e32 v38, v35
	v_add_f32_e32 v35, 1.0, v37
	v_rcp_f32_e32 v39, v35
	v_add_f32_e32 v35, 1.0, v40
	v_rcp_f32_e32 v40, v35
	v_add_f32_e32 v35, 1.0, v41
	v_rcp_f32_e32 v41, v35
	v_pk_mul_f32 v[26:27], v[26:27], v[38:39]
	v_pk_mul_f32 v[28:29], v[28:29], v[40:41]
	s_nop 0
	v_pk_mul_f32 v[28:29], v[32:33], v[28:29]
	v_pk_mul_f32 v[26:27], v[30:31], v[26:27]
	v_pk_fma_f32 v[30:31], v[134:135], v[34:35], v[142:143] op_sel_hi:[1,0,1]
	v_pk_fma_f32 v[32:33], v[136:137], v[34:35], v[144:145] op_sel_hi:[1,0,1]
	v_pk_fma_f32 v[18:19], v[18:19], v[36:37], v[30:31] op_sel_hi:[1,0,1]
	v_pk_fma_f32 v[20:21], v[20:21], v[36:37], v[32:33] op_sel_hi:[1,0,1]
	v_pk_fma_f32 v[30:31], v[132:133], v[34:35], v[140:141] op_sel_hi:[1,0,1]
	v_pk_fma_f32 v[32:33], v[130:131], v[34:35], v[138:139] op_sel_hi:[1,0,1]
	v_pk_fma_f32 v[24:25], v[24:25], v[36:37], v[30:31] op_sel_hi:[1,0,1]
	v_pk_fma_f32 v[22:23], v[22:23], v[36:37], v[32:33] op_sel_hi:[1,0,1]
	v_mul_f32_e32 v30, 0xbfb8aa3b, v18
	v_mul_f32_e32 v31, 0xbfb8aa3b, v19
	v_mul_f32_e32 v32, 0xbfb8aa3b, v20
	v_mul_f32_e32 v33, 0xbfb8aa3b, v21
	v_exp_f32_e32 v30, v30
	v_exp_f32_e32 v31, v31
	v_exp_f32_e32 v32, v32
	v_exp_f32_e32 v33, v33
	v_add_f32_e32 v30, 1.0, v30
	v_add_f32_e32 v31, 1.0, v31
	v_add_f32_e32 v32, 1.0, v32
	v_add_f32_e32 v33, 1.0, v33
	v_rcp_f32_e32 v30, v30
	v_rcp_f32_e32 v31, v31
	v_rcp_f32_e32 v32, v32
	v_rcp_f32_e32 v33, v33
	v_pk_mul_f32 v[18:19], v[18:19], v[30:31]
	v_pk_mul_f32 v[20:21], v[20:21], v[32:33]
	s_nop 0
	v_pk_mul_f32 v[24:25], v[24:25], v[20:21]
	v_pk_mul_f32 v[20:21], v[22:23], v[18:19]
	v_add_u32_e32 v18, 0xa0, v179
	v_mad_i64_i32 v[18:19], s[0:1], v18, s21, v[114:115]
	v_lshl_add_u64 v[22:23], v[18:19], 0, v[116:117]
	v_cvt_pk_bf16_f32 v18, v26, v27
	v_cvt_pk_bf16_f32 v19, v28, v29
	v_cvt_pk_bf16_f32 v20, v20, v21
	v_cvt_pk_bf16_f32 v21, v24, v25
	global_store_dwordx4 v[22:23], v[18:21], off
	ds_read_b64 v[18:19], v180 offset:1408
	s_waitcnt lgkmcnt(0)
; __device__ __forceinline__ f32x4 vsilu(const f32x4& x) { return x * vsig(x); }
; __device__ __forceinline__ void st16_sel(void* p, u32x4 v, bool wt) { if (wt) st16_wt_e(p, v); else *(u32x4*)p = v; }
; __device__ __forceinline__ u32x4 pack8(const f32x4& v0, const f32x4& v1) { u32x4 w; w.x = cvt_pk_bf16(v0[0], v0[1]); w.y = cvt_pk_bf16(v0[2], v0[3]); w.z = cvt_pk_bf16(v1[0], v1[1]); w.w = cvt_pk_bf16(v1[2], v1[3]); return w; }
; __device__ __forceinline__ f32x4 zero4_pk() { f32x2_z a, b; asm volatile("v_pk_mov_b32 %0, 0, 0" : "=v"(a)); asm volatile("v_pk_mov_b32 %0, 0, 0" : "=v"(b)); return (f32x4){a.x, a.y, b.x, b.y}; }
; #define PG8_BAR __builtin_amdgcn_s_barrier()
;     __device__ __forceinline__ void operator()(const f32x4 (&acc)[2][2][4][2], const Unit& u, int wr, int wc, int fr, int fq, int rowmask, const PG8_LAS unsigned char* ev) const {
;     ...
;             for (int m = 0; m < 4; ++m) { if (!((rowmask >> (ai * 4 + m)) & 1)) continue; const int row = row0 + ai * HALF + m * 16; float rA, rB; ln_row_lds(ev, rl0 + ai * HALF + m * 16, rA, rB);
;                 f32x4 v[2];
; #pragma unroll
;                 for (int n = 0; n < 2; ++n) { const f32x4 a = acc[ai][0][m][n] * rA + (k1[0][n] * rB + k2[0][n]), g = acc[ai][1][m][n] * rA + (k1[1][n] * rB + k2[1][n]);
;                     v[n] = vsilu(a) * g; }
;                 st16_sel(H + (size_t)row * 2816 + oc, pack8(v[0], v[1]), (rowmask & 0x200) != 0); }
; template <class Epi, class Sched, bool ALIGN_EPI = false, bool SP2 = false>
; __device__ __forceinline__ void gemm_phase(PG8_LAS unsigned char* lds, const Gemm g, const Sched& S, const Epi& E, int wave_u) {
;     ...
;         if constexpr (!Epi::AFTER_DRAIN) { E(acc, cur, wr, wc, fr, fq, 0xFF, lds + EPV_OFF + (ui & 1) * EPV_BYTES); S.done(cur); }
;         if (!has_next) break;
; #pragma unroll
;         for (int a = 0; a < 2; ++a)
; #pragma unroll
;             for (int b = 0; b < 2; ++b)
; #pragma unroll
;                 for (int m = 0; m < 4; ++m)
; #pragma unroll
;                     for (int n = 0; n < 2; ++n) acc[a][b][m][n] = zero4_pk();
;         cur = nxt; cA = nA; cB = nB; ++ui;
;         if constexpr (ALIGN_EPI) { if (wr == 1) PG8_BAR; }
	v_pk_mul_f32 v[18:19], v[18:19], s[6:7] op_sel_hi:[1,0]
	s_nop 0
	v_fma_f32 v19, -v18, v18, v19
	v_max_f32_e32 v19, 0, v19
	v_add_f32_e32 v19, 0x3727c5ac, v19
	v_rsq_f32_e32 v20, v19
	s_nop 0
	v_mul_f32_e64 v18, v18, -v20
	v_pk_fma_f32 v[22:23], v[154:155], v[18:19], v[158:159] op_sel_hi:[1,0,1]
	v_pk_fma_f32 v[24:25], v[156:157], v[18:19], v[160:161] op_sel_hi:[1,0,1]
	v_pk_fma_f32 v[10:11], v[10:11], v[20:21], v[22:23] op_sel_hi:[1,0,1]
	v_pk_fma_f32 v[12:13], v[12:13], v[20:21], v[24:25] op_sel_hi:[1,0,1]
	v_pk_fma_f32 v[22:23], v[148:149], v[18:19], v[152:153] op_sel_hi:[1,0,1]
	v_pk_fma_f32 v[24:25], v[146:147], v[18:19], v[150:151] op_sel_hi:[1,0,1]
	v_mul_f32_e32 v19, 0xbfb8aa3b, v10
	v_pk_fma_f32 v[14:15], v[14:15], v[20:21], v[24:25] op_sel_hi:[1,0,1]
	v_pk_fma_f32 v[16:17], v[16:17], v[20:21], v[22:23] op_sel_hi:[1,0,1]
	v_exp_f32_e32 v19, v19
	v_mul_f32_e32 v21, 0xbfb8aa3b, v11
	v_exp_f32_e32 v21, v21
	v_mul_f32_e32 v22, 0xbfb8aa3b, v12
	v_exp_f32_e32 v24, v22
	v_mul_f32_e32 v22, 0xbfb8aa3b, v13
	v_exp_f32_e32 v25, v22
	v_add_f32_e32 v19, 1.0, v19
	v_rcp_f32_e32 v22, v19
	v_add_f32_e32 v19, 1.0, v21
	v_rcp_f32_e32 v23, v19
	v_add_f32_e32 v19, 1.0, v24
	v_rcp_f32_e32 v24, v19
	v_add_f32_e32 v19, 1.0, v25
	v_rcp_f32_e32 v25, v19
	v_pk_mul_f32 v[10:11], v[10:11], v[22:23]
	v_pk_mul_f32 v[12:13], v[12:13], v[24:25]
	s_nop 0
	v_pk_mul_f32 v[12:13], v[16:17], v[12:13]
	v_pk_mul_f32 v[10:11], v[14:15], v[10:11]
	v_pk_fma_f32 v[14:15], v[134:135], v[18:19], v[142:143] op_sel_hi:[1,0,1]
	v_pk_fma_f32 v[16:17], v[136:137], v[18:19], v[144:145] op_sel_hi:[1,0,1]
	v_pk_fma_f32 v[2:3], v[2:3], v[20:21], v[14:15] op_sel_hi:[1,0,1]
	v_pk_fma_f32 v[4:5], v[4:5], v[20:21], v[16:17] op_sel_hi:[1,0,1]
	v_pk_fma_f32 v[14:15], v[132:133], v[18:19], v[140:141] op_sel_hi:[1,0,1]
	v_pk_fma_f32 v[16:17], v[130:131], v[18:19], v[138:139] op_sel_hi:[1,0,1]
	v_pk_fma_f32 v[8:9], v[8:9], v[20:21], v[14:15] op_sel_hi:[1,0,1]
	v_pk_fma_f32 v[6:7], v[6:7], v[20:21], v[16:17] op_sel_hi:[1,0,1]
	v_mul_f32_e32 v14, 0xbfb8aa3b, v2
	v_mul_f32_e32 v15, 0xbfb8aa3b, v3
	v_mul_f32_e32 v16, 0xbfb8aa3b, v4
	v_mul_f32_e32 v17, 0xbfb8aa3b, v5
	v_exp_f32_e32 v14, v14
	v_exp_f32_e32 v15, v15
	v_exp_f32_e32 v16, v16
	v_exp_f32_e32 v17, v17
	v_add_f32_e32 v14, 1.0, v14
	v_add_f32_e32 v15, 1.0, v15
	v_add_f32_e32 v16, 1.0, v16
	v_add_f32_e32 v17, 1.0, v17
	v_rcp_f32_e32 v14, v14
	v_rcp_f32_e32 v15, v15
	v_rcp_f32_e32 v16, v16
	v_rcp_f32_e32 v17, v17
	v_pk_mul_f32 v[2:3], v[2:3], v[14:15]
	v_pk_mul_f32 v[4:5], v[4:5], v[16:17]
	s_nop 0
	v_pk_mul_f32 v[8:9], v[8:9], v[4:5]
	v_pk_mul_f32 v[4:5], v[6:7], v[2:3]
	v_add_u32_e32 v2, 0xb0, v179
	v_mad_i64_i32 v[2:3], s[0:1], v2, s21, v[114:115]
	v_lshl_add_u64 v[6:7], v[2:3], 0, v[116:117]
	v_cvt_pk_bf16_f32 v2, v10, v11
	v_cvt_pk_bf16_f32 v3, v12, v13
	v_cvt_pk_bf16_f32 v4, v4, v5
	v_cvt_pk_bf16_f32 v5, v8, v9
	global_store_dwordx4 v[6:7], v[2:5], off
	s_waitcnt vmcnt(8)
	s_cbranch_vccnz .LBB0_1171
	s_andn2_b64 vcc, exec, s[16:17]
	v_pk_mov_b32 v[122:123], 0, 0
	v_pk_mov_b32 v[124:125], 0, 0
	v_pk_mov_b32 v[114:115], 0, 0
	v_pk_mov_b32 v[116:117], 0, 0
	v_pk_mov_b32 v[106:107], 0, 0
	v_pk_mov_b32 v[108:109], 0, 0
	v_pk_mov_b32 v[98:99], 0, 0
	v_pk_mov_b32 v[100:101], 0, 0
	v_pk_mov_b32 v[90:91], 0, 0
	v_pk_mov_b32 v[92:93], 0, 0
	v_pk_mov_b32 v[82:83], 0, 0
	v_pk_mov_b32 v[84:85], 0, 0
	v_pk_mov_b32 v[74:75], 0, 0
	v_pk_mov_b32 v[76:77], 0, 0
	v_pk_mov_b32 v[66:67], 0, 0
	v_pk_mov_b32 v[68:69], 0, 0
	v_pk_mov_b32 v[126:127], 0, 0
	v_pk_mov_b32 v[128:129], 0, 0
	v_pk_mov_b32 v[118:119], 0, 0
	v_pk_mov_b32 v[120:121], 0, 0
	v_pk_mov_b32 v[110:111], 0, 0
	v_pk_mov_b32 v[112:113], 0, 0
	v_pk_mov_b32 v[102:103], 0, 0
	v_pk_mov_b32 v[104:105], 0, 0
	v_pk_mov_b32 v[94:95], 0, 0
	v_pk_mov_b32 v[96:97], 0, 0
	v_pk_mov_b32 v[86:87], 0, 0
	v_pk_mov_b32 v[88:89], 0, 0
	v_pk_mov_b32 v[78:79], 0, 0
	v_pk_mov_b32 v[80:81], 0, 0
	v_pk_mov_b32 v[70:71], 0, 0
	v_pk_mov_b32 v[72:73], 0, 0
	v_pk_mov_b32 v[58:59], 0, 0
	v_pk_mov_b32 v[60:61], 0, 0
	v_pk_mov_b32 v[50:51], 0, 0
	v_pk_mov_b32 v[52:53], 0, 0
	v_pk_mov_b32 v[42:43], 0, 0
	v_pk_mov_b32 v[44:45], 0, 0
	v_pk_mov_b32 v[34:35], 0, 0
	v_pk_mov_b32 v[36:37], 0, 0
	v_pk_mov_b32 v[26:27], 0, 0
	v_pk_mov_b32 v[28:29], 0, 0
	v_pk_mov_b32 v[18:19], 0, 0
	v_pk_mov_b32 v[20:21], 0, 0
	v_pk_mov_b32 v[10:11], 0, 0
	v_pk_mov_b32 v[12:13], 0, 0
	v_pk_mov_b32 v[2:3], 0, 0
	v_pk_mov_b32 v[4:5], 0, 0
	v_pk_mov_b32 v[62:63], 0, 0
	v_pk_mov_b32 v[64:65], 0, 0
	v_pk_mov_b32 v[54:55], 0, 0
	v_pk_mov_b32 v[56:57], 0, 0
	v_pk_mov_b32 v[46:47], 0, 0
	v_pk_mov_b32 v[48:49], 0, 0
	v_pk_mov_b32 v[38:39], 0, 0
	v_pk_mov_b32 v[40:41], 0, 0
	v_pk_mov_b32 v[30:31], 0, 0
	v_pk_mov_b32 v[32:33], 0, 0
	v_pk_mov_b32 v[22:23], 0, 0
	v_pk_mov_b32 v[24:25], 0, 0
	v_pk_mov_b32 v[14:15], 0, 0
	v_pk_mov_b32 v[16:17], 0, 0
	v_pk_mov_b32 v[6:7], 0, 0
	v_pk_mov_b32 v[8:9], 0, 0
	s_cbranch_vccnz .LBB0_1170
	s_barrier
	s_branch .LBB0_1170
